# mixer-C softmax (first query block): bias-table LDS reads hoisted to the top of the tile body; table values shared with the second query block kept in spare registers
# baseline (speedup 1.0000x reference)
; template <int MODE, int NQ, int TS, bool FAST = false> ...
;     ...
;   auto QK = [&](int slot) {
;     const char* kb_ = lds + slot * 16384;
; #pragma unroll
;     for (int nq = 0; nq < NQ; ++nq)
; #pragma unroll
;       for (int r = 0; r < 16; ++r) { s[nq][0][r] = 0.f; s[nq][1][r] = 0.f; }
; #pragma unroll
;     for (int ks = 0; ks < 4; ++ks) {
;       const bf16x8 k0 = *(const bf16x8*)(kb_ + kfo4[ks]), k1 = *(const bf16x8*)(kb_ + kfo4[ks] + 4096);
; #pragma unroll
;       for (int nq = 0; nq < NQ; ++nq) { s[nq][0] = MFMA32(k0, qf[nq][ks], s[nq][0]); s[nq][1] = MFMA32(k1, qf[nq][ks], s[nq][1]); }
;     }
;   };
;   auto SM = [&](int kt) {
; #pragma unroll
;     for (int nq = 0; nq < NQ; ++nq) {
;       f32x16& s0 = s[nq][0]; f32x16& s1 = s[nq][1];
;       float mx = -1e30f;
;       if (MODE == 1) {
;       } else if (MODE == 0 || MODE == 3) {
;         const float* tb = (const float*)(lds + TAB_OFF) + (kt * 64 + 4 * hh - (q0w + 32 * nq + r32) + TAB_ZERO);
; #pragma unroll
;         for (int r = 0; r < 16; ++r) {
;           const float va = fmaf(s0[r], C2, tb[(r & 3) + 8 * (r >> 2)]), vb = fmaf(s1[r], C2, tb[(r & 3) + 8 * (r >> 2) + 32]);
;           s0[r] = va; s1[r] = vb; mx = fmaxf(mx, fmaxf(va, vb));
;         }
;       } else {
;         const float* tb = (const float*)(lds + TAB_OFF) + (wave & 3) * 512 + (kt * 64 + 4 * hh - (q0w + 32 * nq + r32) + 256);
; #pragma unroll
;         for (int r = 0; r < 16; ++r) {
;           const float va = fmaf(s0[r], C2, tb[(r & 3) + 8 * (r >> 2)]), vb = fmaf(s1[r], C2, tb[(r & 3) + 8 * (r >> 2) + 32]);
;           s0[r] = va; s1[r] = vb; mx = fmaxf(mx, fmaxf(va, vb));
;         }
;       }
;       float mn;
;       if (MODE == 1) {
;         mn = sink2;
;       } else {
;         if (__any(mx > m2[nq] + 8.f)) {
;           mx = fmaxf(mx, __shfl_xor(mx, 32));
;           mn = fmaxf(m2[nq], mx);
;           const float alpha = __builtin_amdgcn_exp2f(m2[nq] - mn);
;           l[nq] *= alpha;
; #pragma unroll
;           for (int r = 0; r < 16; ++r) { o[nq][0][r] *= alpha; o[nq][1][r] *= alpha; }
;           m2[nq] = mn;
;         }
;         mn = m2[nq];
;     ...
;   for (int kt = kt0; kt < kt1; ++kt) {
;     { const int tn = (kt + 4 < ktl) ? kt + 4 : ktl; int s4 = slot + 4; if (s4 >= NS) s4 -= NS; ATT_ISSUE(tn, s4); }
;     const bool act = tile_active(kt);
;     if (!g2) {
;       if (act) { QK(slot); SM(kt); PV(slot); }
.LBB0_226:
	s_mov_b32 s28, s0
	s_add_i32 s0, s27, 4
	s_min_i32 s7, s0, s26
	s_cmp_gt_i32 s28, 1
	s_cselect_b32 s0, -2, 4
	s_add_i32 s8, s0, s28
	v_mad_i64_i32 v[98:99], s[0:1], s7, v232, v[172:173]
	s_lshl_b32 s0, s8, 14
	s_add_i32 s8, s16, s0
	v_lshl_add_u64 v[98:99], v[98:99], 0, s[18:19]
	s_mov_b32 m0, s8
	v_add_f32_e32 v0, 0x41000000, v189
	global_load_lds_dwordx4 v[98:99], off
	v_mad_i64_i32 v[98:99], s[0:1], s7, v232, v[174:175]
	v_lshl_add_u64 v[98:99], v[98:99], 0, s[22:23]
	s_add_i32 m0, s8, 0x2000
	s_nop 0
	global_load_lds_dwordx4 v[98:99], off
	s_and_saveexec_b64 s[0:1], s[40:41]
	s_xor_b64 s[0:1], exec, s[0:1]
	s_cbranch_execz .LBB0_232
	ds_read2_b32 v[210:211], v192 offset0:32 offset1:33
	ds_read2_b32 v[212:213], v192 offset0:64 offset1:65
	ds_read2_b32 v[214:215], v192 offset0:34 offset1:35
	ds_read2_b32 v[216:217], v192 offset0:66 offset1:67
	ds_read2_b32 v[218:219], v192 offset0:40 offset1:41
	ds_read2_b32 v[220:221], v192 offset0:72 offset1:73
	ds_read2_b32 v[226:227], v192 offset0:42 offset1:43
	ds_read2_b32 v[228:229], v192 offset0:74 offset1:75
	ds_read2_b32 v[238:239], v192 offset0:48 offset1:49
	ds_read2_b32 v[240:241], v192 offset0:80 offset1:81
	ds_read2_b32 v[242:243], v192 offset0:50 offset1:51
	ds_read2_b32 v[244:245], v192 offset0:82 offset1:83
	ds_read2_b32 v[246:247], v192 offset0:56 offset1:57
	ds_read2_b32 v[248:249], v192 offset0:88 offset1:89
	ds_read2_b32 v[250:251], v192 offset0:58 offset1:59
	s_lshl_b32 s7, s28, 14
	v_or_b32_e32 v70, s7, v191
	ds_read_b128 v[66:69], v70
	ds_read_b128 v[70:73], v70 offset:4096
	v_or_b32_e32 v180, s7, v190
	ds_read_b128 v[176:179], v180
	ds_read_b128 v[194:197], v180 offset:4096
	v_or_b32_e32 v180, s7, v171
	s_waitcnt lgkmcnt(0)
	v_mfma_f32_32x32x16_bf16 v[98:113], v[66:69], v[130:133], 0
	v_mfma_f32_32x32x16_bf16 v[114:129], v[70:73], v[130:133], 0
	v_mfma_f32_32x32x16_bf16 v[82:97], v[66:69], v[146:149], 0
	v_mfma_f32_32x32x16_bf16 v[66:81], v[70:73], v[146:149], 0
	v_mfma_f32_32x32x16_bf16 v[98:113], v[176:179], v[134:137], v[98:113]
	v_mfma_f32_32x32x16_bf16 v[114:129], v[194:197], v[134:137], v[114:129]
	v_mfma_f32_32x32x16_bf16 v[82:97], v[176:179], v[150:153], v[82:97]
	v_mfma_f32_32x32x16_bf16 v[66:81], v[194:197], v[150:153], v[66:81]
	ds_read_b128 v[176:179], v180
	ds_read_b128 v[194:197], v180 offset:4096
	v_or_b32_e32 v180, s7, v167
	s_waitcnt lgkmcnt(0)
	v_mfma_f32_32x32x16_bf16 v[98:113], v[176:179], v[138:141], v[98:113]
	v_mfma_f32_32x32x16_bf16 v[114:129], v[194:197], v[138:141], v[114:129]
	v_mfma_f32_32x32x16_bf16 v[82:97], v[176:179], v[154:157], v[82:97]
	v_mfma_f32_32x32x16_bf16 v[66:81], v[194:197], v[154:157], v[66:81]
	ds_read_b128 v[176:179], v180
	ds_read_b128 v[194:197], v180 offset:4096
	s_waitcnt lgkmcnt(0)
	v_mfma_f32_32x32x16_bf16 v[98:113], v[176:179], v[142:145], v[98:113]
	v_mfma_f32_32x32x16_bf16 v[114:129], v[194:197], v[142:145], v[114:129]
	v_mfma_f32_32x32x16_bf16 v[82:97], v[176:179], v[158:161], v[82:97]
	s_nop 9
	v_fmamk_f32 v193, v98, 0x3e38aa3b, v210
	v_fmamk_f32 v179, v115, 0x3e38aa3b, v213
	v_mfma_f32_32x32x16_bf16 v[66:81], v[194:197], v[158:161], v[66:81]
	v_fmamk_f32 v194, v114, 0x3e38aa3b, v212
	v_fmamk_f32 v178, v99, 0x3e38aa3b, v211
	v_max_f32_e32 v98, v193, v194
	v_max_f32_e32 v99, v178, v179
	v_max3_f32 v180, v98, s12, v99
	v_fmamk_f32 v195, v100, 0x3e38aa3b, v214
	v_fmamk_f32 v196, v116, 0x3e38aa3b, v216
	v_fmamk_f32 v114, v101, 0x3e38aa3b, v215
	v_fmamk_f32 v115, v117, 0x3e38aa3b, v217
	v_max_f32_e32 v100, v195, v196
	v_max_f32_e32 v101, v114, v115
	v_max3_f32 v180, v180, v100, v101
	v_fmamk_f32 v197, v102, 0x3e38aa3b, v218
	v_fmamk_f32 v198, v118, 0x3e38aa3b, v220
	v_fmamk_f32 v116, v103, 0x3e38aa3b, v219
	v_fmamk_f32 v117, v119, 0x3e38aa3b, v221
	v_max_f32_e32 v102, v197, v198
	v_max_f32_e32 v103, v116, v117
	v_max3_f32 v180, v180, v102, v103
	v_fmamk_f32 v199, v104, 0x3e38aa3b, v226
	v_fmamk_f32 v206, v120, 0x3e38aa3b, v228
	v_fmamk_f32 v204, v105, 0x3e38aa3b, v227
	v_fmamk_f32 v119, v121, 0x3e38aa3b, v229
	v_max_f32_e32 v104, v199, v206
	v_max_f32_e32 v105, v204, v119
	v_max3_f32 v180, v180, v104, v105
	v_fmamk_f32 v200, v106, 0x3e38aa3b, v238
	v_fmamk_f32 v201, v122, 0x3e38aa3b, v240
	v_fmamk_f32 v118, v107, 0x3e38aa3b, v239
	v_fmamk_f32 v121, v123, 0x3e38aa3b, v241
	v_max_f32_e32 v106, v200, v201
	v_max_f32_e32 v107, v118, v121
	v_max3_f32 v180, v180, v106, v107
	v_fmamk_f32 v202, v108, 0x3e38aa3b, v242
	v_fmamk_f32 v203, v124, 0x3e38aa3b, v244
	v_fmamk_f32 v120, v109, 0x3e38aa3b, v243
	v_fmamk_f32 v123, v125, 0x3e38aa3b, v245
	v_max_f32_e32 v108, v202, v203
	v_max_f32_e32 v109, v120, v123
	v_max3_f32 v180, v180, v108, v109
	v_fmamk_f32 v205, v110, 0x3e38aa3b, v246
	v_fmamk_f32 v124, v126, 0x3e38aa3b, v248
	v_fmamk_f32 v122, v111, 0x3e38aa3b, v247
	v_fmamk_f32 v125, v127, 0x3e38aa3b, v249
	v_max_f32_e32 v110, v205, v124
	v_max_f32_e32 v111, v122, v125
	v_max3_f32 v180, v180, v110, v111
	ds_read2_b32 v[126:127], v192 offset0:90 offset1:91
	s_waitcnt lgkmcnt(0)
	v_fmamk_f32 v207, v112, 0x3e38aa3b, v250
	v_fmamk_f32 v208, v128, 0x3e38aa3b, v126
	v_fmamk_f32 v126, v113, 0x3e38aa3b, v251
	v_fmac_f32_e32 v127, 0x3e38aa3b, v129
	v_max_f32_e32 v112, v207, v208
	v_max_f32_e32 v113, v126, v127
	v_max3_f32 v112, v180, v112, v113
	v_cmp_gt_f32_e32 vcc, v112, v0
	s_cbranch_vccz .LBB0_229
	v_xor_b32_e32 v0, 32, v223
	v_cmp_lt_i32_e32 vcc, v0, v225
	s_nop 1
	v_cndmask_b32_e32 v0, v223, v0, vcc
	v_lshlrev_b32_e32 v0, 2, v0
	ds_bpermute_b32 v0, v0, v112
	s_waitcnt lgkmcnt(0)
	v_max3_f32 v112, v189, v112, v0
	v_sub_f32_e32 v0, v189, v112
	v_exp_f32_e32 v0, v0
	v_mov_b32_e32 v189, v112
	v_mul_f32_e32 v186, v186, v0
	v_pk_mul_f32 v[64:65], v[64:65], v[0:1] op_sel_hi:[1,0]
	v_pk_mul_f32 v[62:63], v[62:63], v[0:1] op_sel_hi:[1,0]
	v_pk_mul_f32 v[60:61], v[60:61], v[0:1] op_sel_hi:[1,0]
	v_pk_mul_f32 v[58:59], v[58:59], v[0:1] op_sel_hi:[1,0]
	v_pk_mul_f32 v[56:57], v[56:57], v[0:1] op_sel_hi:[1,0]
	v_pk_mul_f32 v[54:55], v[54:55], v[0:1] op_sel_hi:[1,0]
	v_pk_mul_f32 v[52:53], v[52:53], v[0:1] op_sel_hi:[1,0]
	v_pk_mul_f32 v[50:51], v[50:51], v[0:1] op_sel_hi:[1,0]
	v_pk_mul_f32 v[48:49], v[48:49], v[0:1] op_sel_hi:[1,0]
	v_pk_mul_f32 v[46:47], v[46:47], v[0:1] op_sel_hi:[1,0]
	v_pk_mul_f32 v[44:45], v[44:45], v[0:1] op_sel_hi:[1,0]
	v_pk_mul_f32 v[42:43], v[42:43], v[0:1] op_sel_hi:[1,0]
	v_pk_mul_f32 v[40:41], v[40:41], v[0:1] op_sel_hi:[1,0]
	v_pk_mul_f32 v[38:39], v[38:39], v[0:1] op_sel_hi:[1,0]
	v_pk_mul_f32 v[36:37], v[36:37], v[0:1] op_sel_hi:[1,0]
	v_pk_mul_f32 v[34:35], v[34:35], v[0:1] op_sel_hi:[1,0]
; template <int MODE, int NQ, int TS, bool FAST = false> ...
;     ...
;       } else {
;         const float* tb = (const float*)(lds + TAB_OFF) + (wave & 3) * 512 + (kt * 64 + 4 * hh - (q0w + 32 * nq + r32) + 256);
; #pragma unroll
;         for (int r = 0; r < 16; ++r) {
;           const float va = fmaf(s0[r], C2, tb[(r & 3) + 8 * (r >> 2)]), vb = fmaf(s1[r], C2, tb[(r & 3) + 8 * (r >> 2) + 32]);
;           s0[r] = va; s1[r] = vb; mx = fmaxf(mx, fmaxf(va, vb));
;         }
;       }
;       float mn;
;       if (MODE == 1) {
;         mn = sink2;
;       } else {
;         if (__any(mx > m2[nq] + 8.f)) {
;           mx = fmaxf(mx, __shfl_xor(mx, 32));
;           mn = fmaxf(m2[nq], mx);
;           const float alpha = __builtin_amdgcn_exp2f(m2[nq] - mn);
;           l[nq] *= alpha;
; #pragma unroll
;           for (int r = 0; r < 16; ++r) { o[nq][0][r] *= alpha; o[nq][1][r] *= alpha; }
;           m2[nq] = mn;
;         }
;         mn = m2[nq];
.LBB0_229:
	ds_read2_b32 v[112:113], v192 offset1:1
	ds_read2_b32 v[128:129], v192 offset0:2 offset1:3
	ds_read2_b32 v[180:181], v192 offset0:8 offset1:9
	v_fmamk_f32 v176, v66, 0x3e38aa3b, v210
	v_fmamk_f32 v177, v67, 0x3e38aa3b, v211
	s_waitcnt lgkmcnt(0)
	v_fmamk_f32 v0, v82, 0x3e38aa3b, v112
	v_fmamk_f32 v112, v84, 0x3e38aa3b, v128
	v_fmamk_f32 v128, v86, 0x3e38aa3b, v180
	v_fmac_f32_e32 v181, 0x3e38aa3b, v87
	ds_read2_b32 v[86:87], v192 offset0:10 offset1:11
	v_fmac_f32_e32 v113, 0x3e38aa3b, v83
	v_max_f32_e32 v66, v0, v176
	v_max_f32_e32 v67, v113, v177
	v_fmamk_f32 v98, v68, 0x3e38aa3b, v214
	s_waitcnt lgkmcnt(0)
	v_fmamk_f32 v180, v88, 0x3e38aa3b, v86
	v_fmac_f32_e32 v87, 0x3e38aa3b, v89
	ds_read2_b32 v[88:89], v192 offset0:16 offset1:17
	v_fmamk_f32 v86, v72, 0x3e38aa3b, v226
	v_fmac_f32_e32 v129, 0x3e38aa3b, v85
	v_fmamk_f32 v99, v69, 0x3e38aa3b, v215
	v_max3_f32 v66, v66, s12, v67
	s_waitcnt lgkmcnt(0)
	v_fmamk_f32 v102, v90, 0x3e38aa3b, v88
	v_fmac_f32_e32 v89, 0x3e38aa3b, v91
	ds_read2_b32 v[90:91], v192 offset0:18 offset1:19
	v_fmamk_f32 v88, v74, 0x3e38aa3b, v238
	v_max_f32_e32 v67, v112, v98
	v_max_f32_e32 v68, v129, v99
	v_fmamk_f32 v100, v70, 0x3e38aa3b, v218
	s_waitcnt lgkmcnt(0)
	v_fmamk_f32 v104, v92, 0x3e38aa3b, v90
	v_fmac_f32_e32 v91, 0x3e38aa3b, v93
	ds_read2_b32 v[92:93], v192 offset0:24 offset1:25
	v_fmamk_f32 v101, v71, 0x3e38aa3b, v219
	v_fmamk_f32 v109, v79, 0x3e38aa3b, v247
	v_max3_f32 v66, v66, v67, v68
	v_max_f32_e32 v67, v128, v100
	s_waitcnt lgkmcnt(0)
	v_fmamk_f32 v94, v94, 0x3e38aa3b, v92
	v_fmamk_f32 v92, v78, 0x3e38aa3b, v246
	ds_read2_b32 v[78:79], v192 offset0:26 offset1:27
	v_max_f32_e32 v68, v181, v101
	v_fmamk_f32 v103, v73, 0x3e38aa3b, v227
	v_max3_f32 v66, v66, v67, v68
	v_max_f32_e32 v67, v180, v86
	v_max_f32_e32 v68, v87, v103
	v_fmamk_f32 v105, v75, 0x3e38aa3b, v239
	v_max3_f32 v66, v66, v67, v68
	v_max_f32_e32 v67, v102, v88
	v_max_f32_e32 v68, v89, v105
	v_fmamk_f32 v90, v76, 0x3e38aa3b, v242
	v_fmamk_f32 v107, v77, 0x3e38aa3b, v243
	v_max3_f32 v66, v66, v67, v68
	v_max_f32_e32 v67, v104, v90
	v_max_f32_e32 v68, v91, v107
	v_fmac_f32_e32 v93, 0x3e38aa3b, v95
	v_max3_f32 v66, v66, v67, v68
	v_max_f32_e32 v67, v94, v92
	v_max_f32_e32 v68, v93, v109
	s_waitcnt lgkmcnt(0)
	v_fmamk_f32 v95, v96, 0x3e38aa3b, v78
	v_fmamk_f32 v78, v80, 0x3e38aa3b, v250
	v_fmac_f32_e32 v79, 0x3e38aa3b, v97
	v_fmamk_f32 v111, v81, 0x3e38aa3b, v251
	v_max3_f32 v66, v66, v67, v68
	v_max_f32_e32 v67, v95, v78
	v_max_f32_e32 v68, v79, v111
	v_max3_f32 v66, v66, v67, v68
	v_add_f32_e32 v67, 0x41000000, v187
	v_cmp_gt_f32_e32 vcc, v66, v67
	s_cbranch_vccz .LBB0_231
	v_xor_b32_e32 v67, 32, v223
	v_cmp_lt_i32_e32 vcc, v67, v225
	s_nop 1
	v_cndmask_b32_e32 v67, v223, v67, vcc
	v_lshlrev_b32_e32 v67, 2, v67
	ds_bpermute_b32 v67, v67, v66
	s_waitcnt lgkmcnt(0)
	v_max3_f32 v67, v187, v66, v67
	v_sub_f32_e32 v66, v187, v67
	v_exp_f32_e32 v66, v66
	v_mov_b32_e32 v187, v67
	v_mul_f32_e32 v185, v185, v66
	v_pk_mul_f32 v[32:33], v[32:33], v[66:67] op_sel_hi:[1,0]
	v_pk_mul_f32 v[30:31], v[30:31], v[66:67] op_sel_hi:[1,0]
	v_pk_mul_f32 v[28:29], v[28:29], v[66:67] op_sel_hi:[1,0]
	v_pk_mul_f32 v[26:27], v[26:27], v[66:67] op_sel_hi:[1,0]
	v_pk_mul_f32 v[24:25], v[24:25], v[66:67] op_sel_hi:[1,0]
	v_pk_mul_f32 v[22:23], v[22:23], v[66:67] op_sel_hi:[1,0]
	v_pk_mul_f32 v[20:21], v[20:21], v[66:67] op_sel_hi:[1,0]
	v_pk_mul_f32 v[18:19], v[18:19], v[66:67] op_sel_hi:[1,0]
	v_pk_mul_f32 v[16:17], v[16:17], v[66:67] op_sel_hi:[1,0]
	v_pk_mul_f32 v[14:15], v[14:15], v[66:67] op_sel_hi:[1,0]
	v_pk_mul_f32 v[12:13], v[12:13], v[66:67] op_sel_hi:[1,0]
	v_pk_mul_f32 v[10:11], v[10:11], v[66:67] op_sel_hi:[1,0]
	v_pk_mul_f32 v[8:9], v[8:9], v[66:67] op_sel_hi:[1,0]
	v_pk_mul_f32 v[6:7], v[6:7], v[66:67] op_sel_hi:[1,0]
	v_pk_mul_f32 v[4:5], v[4:5], v[66:67] op_sel_hi:[1,0]
	v_pk_mul_f32 v[2:3], v[2:3], v[66:67] op_sel_hi:[1,0]

; #define MFMA32(a, b, c) __builtin_amdgcn_mfma_f32_32x32x16_bf16((a), (b), (c), 0, 0, 0)
; template <int MODE, int NQ, int TS, bool FAST = false> ...
;     ...
;   auto QK = [&](int slot) {
;     const char* kb_ = lds + slot * 16384;
; #pragma unroll
;     for (int nq = 0; nq < NQ; ++nq)
; #pragma unroll
;       for (int r = 0; r < 16; ++r) { s[nq][0][r] = 0.f; s[nq][1][r] = 0.f; }
; #pragma unroll
;     for (int ks = 0; ks < 4; ++ks) {
;       const bf16x8 k0 = *(const bf16x8*)(kb_ + kfo4[ks]), k1 = *(const bf16x8*)(kb_ + kfo4[ks] + 4096);
; #pragma unroll
;       for (int nq = 0; nq < NQ; ++nq) { s[nq][0] = MFMA32(k0, qf[nq][ks], s[nq][0]); s[nq][1] = MFMA32(k1, qf[nq][ks], s[nq][1]); }
;     }
;   };
;   auto SM = [&](int kt) {
; #pragma unroll
;     for (int nq = 0; nq < NQ; ++nq) {
;       f32x16& s0 = s[nq][0]; f32x16& s1 = s[nq][1];
;       float mx = -1e30f;
;       if (MODE == 1) {
;       } else if (MODE == 0 || MODE == 3) {
;         const float* tb = (const float*)(lds + TAB_OFF) + (kt * 64 + 4 * hh - (q0w + 32 * nq + r32) + TAB_ZERO);
; #pragma unroll
;         for (int r = 0; r < 16; ++r) {
;           const float va = fmaf(s0[r], C2, tb[(r & 3) + 8 * (r >> 2)]), vb = fmaf(s1[r], C2, tb[(r & 3) + 8 * (r >> 2) + 32]);
;           s0[r] = va; s1[r] = vb; mx = fmaxf(mx, fmaxf(va, vb));
;         }
;       } else {
;         const float* tb = (const float*)(lds + TAB_OFF) + (wave & 3) * 512 + (kt * 64 + 4 * hh - (q0w + 32 * nq + r32) + 256);
; #pragma unroll
;         for (int r = 0; r < 16; ++r) {
;           const float va = fmaf(s0[r], C2, tb[(r & 3) + 8 * (r >> 2)]), vb = fmaf(s1[r], C2, tb[(r & 3) + 8 * (r >> 2) + 32]);
;           s0[r] = va; s1[r] = vb; mx = fmaxf(mx, fmaxf(va, vb));
;         }
;       }
;       float mn;
;       if (MODE == 1) {
;         mn = sink2;
;       } else {
;         if (__any(mx > m2[nq] + 8.f)) {
;           mx = fmaxf(mx, __shfl_xor(mx, 32));
;           mn = fmaxf(m2[nq], mx);
;           const float alpha = __builtin_amdgcn_exp2f(m2[nq] - mn);
;           l[nq] *= alpha;
; #pragma unroll
;           for (int r = 0; r < 16; ++r) { o[nq][0][r] *= alpha; o[nq][1][r] *= alpha; }
;           m2[nq] = mn;
;         }
;         mn = m2[nq];
;     ...
;       if (act) { QK(slot); SM(kt); }
.LBB0_235:
	ds_read2_b32 v[210:211], v192 offset0:32 offset1:33
	ds_read2_b32 v[212:213], v192 offset0:64 offset1:65
	ds_read2_b32 v[214:215], v192 offset0:34 offset1:35
	ds_read2_b32 v[216:217], v192 offset0:66 offset1:67
	ds_read2_b32 v[218:219], v192 offset0:40 offset1:41
	ds_read2_b32 v[220:221], v192 offset0:72 offset1:73
	ds_read2_b32 v[226:227], v192 offset0:42 offset1:43
	ds_read2_b32 v[228:229], v192 offset0:74 offset1:75
	ds_read2_b32 v[238:239], v192 offset0:48 offset1:49
	ds_read2_b32 v[240:241], v192 offset0:80 offset1:81
	ds_read2_b32 v[242:243], v192 offset0:50 offset1:51
	ds_read2_b32 v[244:245], v192 offset0:82 offset1:83
	ds_read2_b32 v[246:247], v192 offset0:56 offset1:57
	ds_read2_b32 v[248:249], v192 offset0:88 offset1:89
	ds_read2_b32 v[250:251], v192 offset0:58 offset1:59
	s_lshl_b32 s6, s28, 14
	v_or_b32_e32 v70, s6, v191
	ds_read_b128 v[66:69], v70
	ds_read_b128 v[70:73], v70 offset:4096
	v_or_b32_e32 v180, s6, v190
	ds_read_b128 v[176:179], v180
	ds_read_b128 v[194:197], v180 offset:4096
	v_or_b32_e32 v180, s6, v171
	s_waitcnt lgkmcnt(0)
	v_mfma_f32_32x32x16_bf16 v[98:113], v[66:69], v[130:133], 0
	v_mfma_f32_32x32x16_bf16 v[114:129], v[70:73], v[130:133], 0
	v_mfma_f32_32x32x16_bf16 v[82:97], v[66:69], v[146:149], 0
	v_mfma_f32_32x32x16_bf16 v[66:81], v[70:73], v[146:149], 0
	v_mfma_f32_32x32x16_bf16 v[98:113], v[176:179], v[134:137], v[98:113]
	v_mfma_f32_32x32x16_bf16 v[114:129], v[194:197], v[134:137], v[114:129]
	v_mfma_f32_32x32x16_bf16 v[82:97], v[176:179], v[150:153], v[82:97]
	v_mfma_f32_32x32x16_bf16 v[66:81], v[194:197], v[150:153], v[66:81]
	ds_read_b128 v[176:179], v180
	ds_read_b128 v[194:197], v180 offset:4096
	v_or_b32_e32 v180, s6, v167
	s_waitcnt lgkmcnt(0)
	v_mfma_f32_32x32x16_bf16 v[98:113], v[176:179], v[138:141], v[98:113]
	v_mfma_f32_32x32x16_bf16 v[114:129], v[194:197], v[138:141], v[114:129]
	v_mfma_f32_32x32x16_bf16 v[82:97], v[176:179], v[154:157], v[82:97]
	v_mfma_f32_32x32x16_bf16 v[66:81], v[194:197], v[154:157], v[66:81]
	ds_read_b128 v[176:179], v180
	ds_read_b128 v[194:197], v180 offset:4096
	s_waitcnt lgkmcnt(0)
	v_mfma_f32_32x32x16_bf16 v[98:113], v[176:179], v[142:145], v[98:113]
	v_mfma_f32_32x32x16_bf16 v[114:129], v[194:197], v[142:145], v[114:129]
	v_mfma_f32_32x32x16_bf16 v[82:97], v[176:179], v[158:161], v[82:97]
	s_nop 9
	v_fmamk_f32 v180, v98, 0x3e38aa3b, v210
	v_fmamk_f32 v181, v114, 0x3e38aa3b, v212
	v_fmamk_f32 v178, v99, 0x3e38aa3b, v211
	v_fmamk_f32 v179, v115, 0x3e38aa3b, v213
	v_max_f32_e32 v98, v180, v181
	v_max_f32_e32 v99, v178, v179
	v_mfma_f32_32x32x16_bf16 v[66:81], v[194:197], v[158:161], v[66:81]
	v_max3_f32 v195, v98, s12, v99
	v_fmamk_f32 v193, v100, 0x3e38aa3b, v214
	v_fmamk_f32 v194, v116, 0x3e38aa3b, v216
	v_fmamk_f32 v114, v101, 0x3e38aa3b, v215
	v_fmamk_f32 v115, v117, 0x3e38aa3b, v217
	v_max_f32_e32 v100, v193, v194
	v_max_f32_e32 v101, v114, v115
	v_max3_f32 v197, v195, v100, v101
	v_fmamk_f32 v195, v102, 0x3e38aa3b, v218
	v_fmamk_f32 v196, v118, 0x3e38aa3b, v220
	v_fmamk_f32 v116, v103, 0x3e38aa3b, v219
	v_fmamk_f32 v117, v119, 0x3e38aa3b, v221
	v_max_f32_e32 v102, v195, v196
	v_max_f32_e32 v103, v116, v117
	v_max3_f32 v198, v197, v102, v103
	v_fmamk_f32 v197, v104, 0x3e38aa3b, v226
	v_fmamk_f32 v200, v120, 0x3e38aa3b, v228
	v_fmamk_f32 v199, v105, 0x3e38aa3b, v227
	v_fmamk_f32 v119, v121, 0x3e38aa3b, v229
	v_max_f32_e32 v104, v197, v200
	v_max_f32_e32 v105, v199, v119
	v_max3_f32 v201, v198, v104, v105
	v_fmamk_f32 v198, v106, 0x3e38aa3b, v238
	v_fmamk_f32 v120, v122, 0x3e38aa3b, v240
	v_fmamk_f32 v118, v107, 0x3e38aa3b, v239
	v_fmamk_f32 v121, v123, 0x3e38aa3b, v241
	v_max_f32_e32 v106, v198, v120
	v_max_f32_e32 v107, v118, v121
	v_max3_f32 v203, v201, v106, v107
	v_fmamk_f32 v201, v108, 0x3e38aa3b, v242
	v_fmamk_f32 v202, v124, 0x3e38aa3b, v244
	v_fmamk_f32 v122, v109, 0x3e38aa3b, v243
	v_fmamk_f32 v123, v125, 0x3e38aa3b, v245
	v_max_f32_e32 v108, v201, v202
	v_max_f32_e32 v109, v122, v123
	v_max3_f32 v205, v203, v108, v109
	v_fmamk_f32 v203, v110, 0x3e38aa3b, v246
	v_fmamk_f32 v204, v126, 0x3e38aa3b, v248
	v_fmamk_f32 v124, v111, 0x3e38aa3b, v247
	v_fmamk_f32 v125, v127, 0x3e38aa3b, v249
	v_max_f32_e32 v110, v203, v204
	v_max_f32_e32 v111, v124, v125
	v_max3_f32 v206, v205, v110, v111
	ds_read2_b32 v[126:127], v192 offset0:90 offset1:91
	s_waitcnt lgkmcnt(0)
	v_fmamk_f32 v205, v112, 0x3e38aa3b, v250
	v_fmamk_f32 v128, v128, 0x3e38aa3b, v126
	v_fmamk_f32 v126, v113, 0x3e38aa3b, v251
	v_fmac_f32_e32 v127, 0x3e38aa3b, v129
	v_max_f32_e32 v112, v205, v128
	v_max_f32_e32 v113, v126, v127
	v_max3_f32 v112, v206, v112, v113
	v_cmp_gt_f32_e32 vcc, v112, v0
	s_cbranch_vccz .LBB0_237
	v_xor_b32_e32 v0, 32, v223
	v_cmp_lt_i32_e32 vcc, v0, v225
	s_nop 1
	v_cndmask_b32_e32 v0, v223, v0, vcc
	v_lshlrev_b32_e32 v0, 2, v0
	ds_bpermute_b32 v0, v0, v112
	s_waitcnt lgkmcnt(0)
	v_max3_f32 v112, v189, v112, v0
	v_sub_f32_e32 v0, v189, v112
	v_exp_f32_e32 v0, v0
	v_mov_b32_e32 v189, v112
	v_mul_f32_e32 v186, v186, v0
	v_pk_mul_f32 v[64:65], v[64:65], v[0:1] op_sel_hi:[1,0]
	v_pk_mul_f32 v[62:63], v[62:63], v[0:1] op_sel_hi:[1,0]
	v_pk_mul_f32 v[60:61], v[60:61], v[0:1] op_sel_hi:[1,0]
	v_pk_mul_f32 v[58:59], v[58:59], v[0:1] op_sel_hi:[1,0]
	v_pk_mul_f32 v[56:57], v[56:57], v[0:1] op_sel_hi:[1,0]
	v_pk_mul_f32 v[54:55], v[54:55], v[0:1] op_sel_hi:[1,0]
	v_pk_mul_f32 v[52:53], v[52:53], v[0:1] op_sel_hi:[1,0]
	v_pk_mul_f32 v[50:51], v[50:51], v[0:1] op_sel_hi:[1,0]
	v_pk_mul_f32 v[48:49], v[48:49], v[0:1] op_sel_hi:[1,0]
	v_pk_mul_f32 v[46:47], v[46:47], v[0:1] op_sel_hi:[1,0]
	v_pk_mul_f32 v[44:45], v[44:45], v[0:1] op_sel_hi:[1,0]
	v_pk_mul_f32 v[42:43], v[42:43], v[0:1] op_sel_hi:[1,0]
	v_pk_mul_f32 v[40:41], v[40:41], v[0:1] op_sel_hi:[1,0]
	v_pk_mul_f32 v[38:39], v[38:39], v[0:1] op_sel_hi:[1,0]
	v_pk_mul_f32 v[36:37], v[36:37], v[0:1] op_sel_hi:[1,0]
	v_pk_mul_f32 v[34:35], v[34:35], v[0:1] op_sel_hi:[1,0]
; template <int MODE, int NQ, int TS, bool FAST = false> ...
;     ...
;       } else {
;         const float* tb = (const float*)(lds + TAB_OFF) + (wave & 3) * 512 + (kt * 64 + 4 * hh - (q0w + 32 * nq + r32) + 256);
; #pragma unroll
;         for (int r = 0; r < 16; ++r) {
;           const float va = fmaf(s0[r], C2, tb[(r & 3) + 8 * (r >> 2)]), vb = fmaf(s1[r], C2, tb[(r & 3) + 8 * (r >> 2) + 32]);
;           s0[r] = va; s1[r] = vb; mx = fmaxf(mx, fmaxf(va, vb));
;         }
;       }
;       float mn;
;       if (MODE == 1) {
;         mn = sink2;
;       } else {
;         if (__any(mx > m2[nq] + 8.f)) {
;           mx = fmaxf(mx, __shfl_xor(mx, 32));
;           mn = fmaxf(m2[nq], mx);
;           const float alpha = __builtin_amdgcn_exp2f(m2[nq] - mn);
;           l[nq] *= alpha;
; #pragma unroll
;           for (int r = 0; r < 16; ++r) { o[nq][0][r] *= alpha; o[nq][1][r] *= alpha; }
;           m2[nq] = mn;
;         }
;         mn = m2[nq];
.LBB0_237:
	ds_read2_b32 v[112:113], v192 offset1:1
	v_fmamk_f32 v177, v67, 0x3e38aa3b, v211
	v_fmamk_f32 v99, v69, 0x3e38aa3b, v215
	v_fmamk_f32 v101, v71, 0x3e38aa3b, v219
	v_fmamk_f32 v109, v79, 0x3e38aa3b, v247
	s_waitcnt lgkmcnt(0)
	v_fmamk_f32 v0, v82, 0x3e38aa3b, v112
	v_fmamk_f32 v82, v66, 0x3e38aa3b, v210
	v_fmac_f32_e32 v113, 0x3e38aa3b, v83
	v_max_f32_e32 v66, v0, v82
	v_max_f32_e32 v67, v113, v177
	v_max3_f32 v83, v66, s12, v67
	ds_read2_b32 v[66:67], v192 offset0:2 offset1:3
	v_fmamk_f32 v72, v72, 0x3e38aa3b, v226
	v_fmamk_f32 v103, v73, 0x3e38aa3b, v227
	v_fmamk_f32 v74, v74, 0x3e38aa3b, v238
	v_fmamk_f32 v105, v75, 0x3e38aa3b, v239
	s_waitcnt lgkmcnt(0)
	v_fmamk_f32 v84, v84, 0x3e38aa3b, v66
	v_fmamk_f32 v66, v68, 0x3e38aa3b, v214
	v_fmac_f32_e32 v67, 0x3e38aa3b, v85
	v_max_f32_e32 v68, v84, v66
	v_max_f32_e32 v69, v67, v99
	v_max3_f32 v83, v83, v68, v69
	ds_read2_b32 v[68:69], v192 offset0:8 offset1:9
	v_fmamk_f32 v76, v76, 0x3e38aa3b, v242
	v_fmamk_f32 v107, v77, 0x3e38aa3b, v243
	v_fmamk_f32 v111, v81, 0x3e38aa3b, v251
	s_waitcnt lgkmcnt(0)
	v_fmamk_f32 v98, v86, 0x3e38aa3b, v68
	v_fmac_f32_e32 v69, 0x3e38aa3b, v87
	ds_read2_b32 v[86:87], v192 offset0:10 offset1:11
	v_fmamk_f32 v68, v70, 0x3e38aa3b, v218
	v_max_f32_e32 v70, v98, v68
	v_max_f32_e32 v71, v69, v101
	v_max3_f32 v70, v83, v70, v71
	s_waitcnt lgkmcnt(0)
	v_fmamk_f32 v100, v88, 0x3e38aa3b, v86
	v_fmac_f32_e32 v87, 0x3e38aa3b, v89
	ds_read2_b32 v[88:89], v192 offset0:16 offset1:17
	v_max_f32_e32 v71, v100, v72
	v_max_f32_e32 v73, v87, v103
	v_max3_f32 v70, v70, v71, v73
	s_waitcnt lgkmcnt(0)
	v_fmamk_f32 v86, v90, 0x3e38aa3b, v88
	v_fmac_f32_e32 v89, 0x3e38aa3b, v91
	ds_read2_b32 v[90:91], v192 offset0:18 offset1:19
	v_max_f32_e32 v71, v86, v74
	v_max_f32_e32 v73, v89, v105
	v_max3_f32 v70, v70, v71, v73
	s_waitcnt lgkmcnt(0)
	v_fmamk_f32 v88, v92, 0x3e38aa3b, v90
	v_fmac_f32_e32 v91, 0x3e38aa3b, v93
	ds_read2_b32 v[92:93], v192 offset0:24 offset1:25
	v_fmamk_f32 v90, v78, 0x3e38aa3b, v246
	ds_read2_b32 v[78:79], v192 offset0:26 offset1:27
	v_max_f32_e32 v71, v88, v76
	v_max_f32_e32 v73, v91, v107
	s_waitcnt lgkmcnt(0)
	v_fmamk_f32 v92, v94, 0x3e38aa3b, v92
	v_fmac_f32_e32 v93, 0x3e38aa3b, v95
	v_max3_f32 v70, v70, v71, v73
	v_max_f32_e32 v71, v92, v90
	v_max_f32_e32 v73, v93, v109
	v_fmamk_f32 v94, v96, 0x3e38aa3b, v78
	v_fmamk_f32 v78, v80, 0x3e38aa3b, v250
	v_fmac_f32_e32 v79, 0x3e38aa3b, v97
	v_max3_f32 v70, v70, v71, v73
	v_max_f32_e32 v71, v94, v78
	v_max_f32_e32 v73, v79, v111
	v_max3_f32 v70, v70, v71, v73
	v_add_f32_e32 v71, 0x41000000, v187
	v_cmp_gt_f32_e32 vcc, v70, v71
	s_cbranch_vccz .LBB0_239
	v_xor_b32_e32 v71, 32, v223
	v_cmp_lt_i32_e32 vcc, v71, v225
	s_nop 1
	v_cndmask_b32_e32 v71, v223, v71, vcc
	v_lshlrev_b32_e32 v71, 2, v71
	ds_bpermute_b32 v71, v71, v70
	s_waitcnt lgkmcnt(0)
	v_max3_f32 v71, v187, v70, v71
	v_sub_f32_e32 v70, v187, v71
	v_exp_f32_e32 v70, v70
	v_mov_b32_e32 v187, v71
	v_mul_f32_e32 v185, v185, v70
	v_pk_mul_f32 v[32:33], v[32:33], v[70:71] op_sel_hi:[1,0]
	v_pk_mul_f32 v[30:31], v[30:31], v[70:71] op_sel_hi:[1,0]
	v_pk_mul_f32 v[28:29], v[28:29], v[70:71] op_sel_hi:[1,0]
	v_pk_mul_f32 v[26:27], v[26:27], v[70:71] op_sel_hi:[1,0]
	v_pk_mul_f32 v[24:25], v[24:25], v[70:71] op_sel_hi:[1,0]
	v_pk_mul_f32 v[22:23], v[22:23], v[70:71] op_sel_hi:[1,0]
	v_pk_mul_f32 v[20:21], v[20:21], v[70:71] op_sel_hi:[1,0]
	v_pk_mul_f32 v[18:19], v[18:19], v[70:71] op_sel_hi:[1,0]
	v_pk_mul_f32 v[16:17], v[16:17], v[70:71] op_sel_hi:[1,0]
	v_pk_mul_f32 v[14:15], v[14:15], v[70:71] op_sel_hi:[1,0]
	v_pk_mul_f32 v[12:13], v[12:13], v[70:71] op_sel_hi:[1,0]
	v_pk_mul_f32 v[10:11], v[10:11], v[70:71] op_sel_hi:[1,0]
	v_pk_mul_f32 v[8:9], v[8:9], v[70:71] op_sel_hi:[1,0]
	v_pk_mul_f32 v[6:7], v[6:7], v[70:71] op_sel_hi:[1,0]
	v_pk_mul_f32 v[4:5], v[4:5], v[70:71] op_sel_hi:[1,0]
	v_pk_mul_f32 v[2:3], v[2:3], v[70:71] op_sel_hi:[1,0]
